# GEMM cores: each wave refills its own A rows right after reading them (before the B reads and the barrier); A fragments read before the slab barrier
# speedup vs baseline: 1.0209x; 1.0001x over previous
.Lg3_ood_loop:
	s_waitcnt vmcnt(0)
	ds_read_b128 v[196:199], v243
	ds_read_b128 v[200:203], v243 offset:2048
	ds_read_b128 v[204:207], v243 offset:4096
	ds_read_b128 v[216:219], v243 offset:6144
	ds_read_b128 v[226:229], v244
	ds_read_b128 v[230:233], v244 offset:2048
	ds_read_b128 v[234:237], v244 offset:4096
	ds_read_b128 v[238:241], v244 offset:6144
	s_barrier
	ds_read_b128 v[118:121], v245
	ds_read_b128 v[122:125], v245 offset:2048
	ds_read_b128 v[126:129], v245 offset:4096
	ds_read_b128 v[130:133], v245 offset:6144
	ds_read_b128 v[138:141], v245 offset:8192
	ds_read_b128 v[142:145], v245 offset:10240
	ds_read_b128 v[150:153], v245 offset:12288
	ds_read_b128 v[154:157], v245 offset:14336
	ds_read_b128 v[158:161], v246
	ds_read_b128 v[162:165], v246 offset:2048
	ds_read_b128 v[170:173], v246 offset:4096
	ds_read_b128 v[174:177], v246 offset:6144
	ds_read_b128 v[180:183], v246 offset:8192
	ds_read_b128 v[184:187], v246 offset:10240
	ds_read_b128 v[188:191], v246 offset:12288
	ds_read_b128 v[192:195], v246 offset:14336
	s_waitcnt lgkmcnt(8)
	s_mov_b32 m0, s32
	s_nop 0
	global_load_lds_dwordx4 v0, s[50:51]
	s_add_u32 m0, s32, 1024
	s_nop 0
	global_load_lds_dwordx4 v208, s[50:51]
	s_add_u32 m0, s32, 2048
	s_nop 0
	global_load_lds_dwordx4 v0, s[52:53]
	s_add_u32 m0, s32, 3072
	s_nop 0
	global_load_lds_dwordx4 v208, s[52:53]
	s_add_u32 m0, s32, 4096
	s_nop 0
	global_load_lds_dwordx4 v0, s[54:55]
	s_add_u32 m0, s32, 5120
	s_nop 0
	global_load_lds_dwordx4 v208, s[54:55]
	s_add_u32 m0, s32, 6144
	s_nop 0
	global_load_lds_dwordx4 v0, s[56:57]
	s_add_u32 m0, s32, 7168
	s_nop 0
	global_load_lds_dwordx4 v208, s[56:57]
	s_add_u32 s50, s50, 0x80
	s_addc_u32 s51, s51, 0
	s_add_u32 s52, s52, 0x80
	s_addc_u32 s53, s53, 0
	s_add_u32 s54, s54, 0x80
	s_addc_u32 s55, s55, 0
	s_add_u32 s56, s56, 0x80
	s_addc_u32 s57, s57, 0
	s_waitcnt lgkmcnt(0)
	s_barrier
	s_mov_b32 m0, s47
	s_nop 0
	global_load_lds_dwordx4 v209, s[58:59]
	s_add_u32 m0, s47, 1024
	s_nop 0
	global_load_lds_dwordx4 v242, s[58:59]
	s_add_u32 m0, s47, 2048
	s_nop 0
	global_load_lds_dwordx4 v209, s[60:61]
	s_add_u32 m0, s47, 3072
	s_nop 0
	global_load_lds_dwordx4 v242, s[60:61]
	s_add_u32 s58, s58, 0x80
	s_addc_u32 s59, s59, 0
	s_add_u32 s60, s60, 0x80
	s_addc_u32 s61, s61, 0
	v_mfma_f32_16x16x32_bf16 v[166:169], v[118:121], v[196:199], v[166:169]
	v_mfma_f32_16x16x32_bf16 v[94:97], v[118:121], v[200:203], v[94:97]
	v_mfma_f32_16x16x32_bf16 v[62:65], v[118:121], v[204:207], v[62:65]
	v_mfma_f32_16x16x32_bf16 v[30:33], v[118:121], v[216:219], v[30:33]
	v_mfma_f32_16x16x32_bf16 v[146:149], v[122:125], v[196:199], v[146:149]
	v_mfma_f32_16x16x32_bf16 v[90:93], v[122:125], v[200:203], v[90:93]
	v_mfma_f32_16x16x32_bf16 v[58:61], v[122:125], v[204:207], v[58:61]
	v_mfma_f32_16x16x32_bf16 v[26:29], v[122:125], v[216:219], v[26:29]
	v_mfma_f32_16x16x32_bf16 v[134:137], v[126:129], v[196:199], v[134:137]
	v_mfma_f32_16x16x32_bf16 v[86:89], v[126:129], v[200:203], v[86:89]
	v_mfma_f32_16x16x32_bf16 v[54:57], v[126:129], v[204:207], v[54:57]
	v_mfma_f32_16x16x32_bf16 v[22:25], v[126:129], v[216:219], v[22:25]
	v_mfma_f32_16x16x32_bf16 v[114:117], v[130:133], v[196:199], v[114:117]
	v_mfma_f32_16x16x32_bf16 v[82:85], v[130:133], v[200:203], v[82:85]
	v_mfma_f32_16x16x32_bf16 v[50:53], v[130:133], v[204:207], v[50:53]
	v_mfma_f32_16x16x32_bf16 v[18:21], v[130:133], v[216:219], v[18:21]
	v_mfma_f32_16x16x32_bf16 v[110:113], v[138:141], v[196:199], v[110:113]
	v_mfma_f32_16x16x32_bf16 v[78:81], v[138:141], v[200:203], v[78:81]
	v_mfma_f32_16x16x32_bf16 v[46:49], v[138:141], v[204:207], v[46:49]
	v_mfma_f32_16x16x32_bf16 v[14:17], v[138:141], v[216:219], v[14:17]
	v_mfma_f32_16x16x32_bf16 v[106:109], v[142:145], v[196:199], v[106:109]
	v_mfma_f32_16x16x32_bf16 v[74:77], v[142:145], v[200:203], v[74:77]
	v_mfma_f32_16x16x32_bf16 v[42:45], v[142:145], v[204:207], v[42:45]
	v_mfma_f32_16x16x32_bf16 v[10:13], v[142:145], v[216:219], v[10:13]
	v_mfma_f32_16x16x32_bf16 v[102:105], v[150:153], v[196:199], v[102:105]
	v_mfma_f32_16x16x32_bf16 v[70:73], v[150:153], v[200:203], v[70:73]
	v_mfma_f32_16x16x32_bf16 v[38:41], v[150:153], v[204:207], v[38:41]
	v_mfma_f32_16x16x32_bf16 v[6:9], v[150:153], v[216:219], v[6:9]
	v_mfma_f32_16x16x32_bf16 v[98:101], v[154:157], v[196:199], v[98:101]
	v_mfma_f32_16x16x32_bf16 v[66:69], v[154:157], v[200:203], v[66:69]
	v_mfma_f32_16x16x32_bf16 v[34:37], v[154:157], v[204:207], v[34:37]
	v_mfma_f32_16x16x32_bf16 v[2:5], v[154:157], v[216:219], v[2:5]
	v_mfma_f32_16x16x32_bf16 v[166:169], v[158:161], v[226:229], v[166:169]
	v_mfma_f32_16x16x32_bf16 v[94:97], v[158:161], v[230:233], v[94:97]
	v_mfma_f32_16x16x32_bf16 v[62:65], v[158:161], v[234:237], v[62:65]
	v_mfma_f32_16x16x32_bf16 v[30:33], v[158:161], v[238:241], v[30:33]
	v_mfma_f32_16x16x32_bf16 v[146:149], v[162:165], v[226:229], v[146:149]
	v_mfma_f32_16x16x32_bf16 v[90:93], v[162:165], v[230:233], v[90:93]
	v_mfma_f32_16x16x32_bf16 v[58:61], v[162:165], v[234:237], v[58:61]
	v_mfma_f32_16x16x32_bf16 v[26:29], v[162:165], v[238:241], v[26:29]
	v_mfma_f32_16x16x32_bf16 v[134:137], v[170:173], v[226:229], v[134:137]
	v_mfma_f32_16x16x32_bf16 v[86:89], v[170:173], v[230:233], v[86:89]
	v_mfma_f32_16x16x32_bf16 v[54:57], v[170:173], v[234:237], v[54:57]
	v_mfma_f32_16x16x32_bf16 v[22:25], v[170:173], v[238:241], v[22:25]
	v_mfma_f32_16x16x32_bf16 v[114:117], v[174:177], v[226:229], v[114:117]
	v_mfma_f32_16x16x32_bf16 v[82:85], v[174:177], v[230:233], v[82:85]
	v_mfma_f32_16x16x32_bf16 v[50:53], v[174:177], v[234:237], v[50:53]
	v_mfma_f32_16x16x32_bf16 v[18:21], v[174:177], v[238:241], v[18:21]
	v_mfma_f32_16x16x32_bf16 v[110:113], v[180:183], v[226:229], v[110:113]
	v_mfma_f32_16x16x32_bf16 v[78:81], v[180:183], v[230:233], v[78:81]
	v_mfma_f32_16x16x32_bf16 v[46:49], v[180:183], v[234:237], v[46:49]
	v_mfma_f32_16x16x32_bf16 v[14:17], v[180:183], v[238:241], v[14:17]
	v_mfma_f32_16x16x32_bf16 v[106:109], v[184:187], v[226:229], v[106:109]
	v_mfma_f32_16x16x32_bf16 v[74:77], v[184:187], v[230:233], v[74:77]
	v_mfma_f32_16x16x32_bf16 v[42:45], v[184:187], v[234:237], v[42:45]
	v_mfma_f32_16x16x32_bf16 v[10:13], v[184:187], v[238:241], v[10:13]
	v_mfma_f32_16x16x32_bf16 v[102:105], v[188:191], v[226:229], v[102:105]
	v_mfma_f32_16x16x32_bf16 v[70:73], v[188:191], v[230:233], v[70:73]
	v_mfma_f32_16x16x32_bf16 v[38:41], v[188:191], v[234:237], v[38:41]
	v_mfma_f32_16x16x32_bf16 v[6:9], v[188:191], v[238:241], v[6:9]
	v_mfma_f32_16x16x32_bf16 v[98:101], v[192:195], v[226:229], v[98:101]
	v_mfma_f32_16x16x32_bf16 v[66:69], v[192:195], v[230:233], v[66:69]
	v_mfma_f32_16x16x32_bf16 v[34:37], v[192:195], v[234:237], v[34:37]
	v_mfma_f32_16x16x32_bf16 v[2:5], v[192:195], v[238:241], v[2:5]
	s_sub_u32 s49, s49, 1
	s_cmp_lg_u32 s49, 0
	s_cbranch_scc1 .Lg3_ood_loop
	s_waitcnt vmcnt(0)
	ds_read_b128 v[196:199], v243
	ds_read_b128 v[200:203], v243 offset:2048
	ds_read_b128 v[204:207], v243 offset:4096
	ds_read_b128 v[216:219], v243 offset:6144
	ds_read_b128 v[226:229], v244
	ds_read_b128 v[230:233], v244 offset:2048
	ds_read_b128 v[234:237], v244 offset:4096
	ds_read_b128 v[238:241], v244 offset:6144
	s_barrier
	ds_read_b128 v[118:121], v245
	ds_read_b128 v[122:125], v245 offset:2048
	ds_read_b128 v[126:129], v245 offset:4096
	ds_read_b128 v[130:133], v245 offset:6144
	ds_read_b128 v[138:141], v245 offset:8192
	ds_read_b128 v[142:145], v245 offset:10240
	ds_read_b128 v[150:153], v245 offset:12288
	ds_read_b128 v[154:157], v245 offset:14336
	ds_read_b128 v[158:161], v246
	ds_read_b128 v[162:165], v246 offset:2048
	ds_read_b128 v[170:173], v246 offset:4096
	ds_read_b128 v[174:177], v246 offset:6144
	ds_read_b128 v[180:183], v246 offset:8192
	ds_read_b128 v[184:187], v246 offset:10240
	ds_read_b128 v[188:191], v246 offset:12288
	ds_read_b128 v[192:195], v246 offset:14336
	s_waitcnt lgkmcnt(8)
	s_waitcnt lgkmcnt(0)
	s_barrier
	v_mfma_f32_16x16x32_bf16 v[166:169], v[118:121], v[196:199], v[166:169]
	v_mfma_f32_16x16x32_bf16 v[94:97], v[118:121], v[200:203], v[94:97]
	v_mfma_f32_16x16x32_bf16 v[62:65], v[118:121], v[204:207], v[62:65]
	v_mfma_f32_16x16x32_bf16 v[30:33], v[118:121], v[216:219], v[30:33]
	v_mfma_f32_16x16x32_bf16 v[146:149], v[122:125], v[196:199], v[146:149]
	v_mfma_f32_16x16x32_bf16 v[90:93], v[122:125], v[200:203], v[90:93]
	v_mfma_f32_16x16x32_bf16 v[58:61], v[122:125], v[204:207], v[58:61]
	v_mfma_f32_16x16x32_bf16 v[26:29], v[122:125], v[216:219], v[26:29]
	v_mfma_f32_16x16x32_bf16 v[134:137], v[126:129], v[196:199], v[134:137]
	v_mfma_f32_16x16x32_bf16 v[86:89], v[126:129], v[200:203], v[86:89]
	v_mfma_f32_16x16x32_bf16 v[54:57], v[126:129], v[204:207], v[54:57]
	v_mfma_f32_16x16x32_bf16 v[22:25], v[126:129], v[216:219], v[22:25]
	v_mfma_f32_16x16x32_bf16 v[114:117], v[130:133], v[196:199], v[114:117]
	v_mfma_f32_16x16x32_bf16 v[82:85], v[130:133], v[200:203], v[82:85]
	v_mfma_f32_16x16x32_bf16 v[50:53], v[130:133], v[204:207], v[50:53]
	v_mfma_f32_16x16x32_bf16 v[18:21], v[130:133], v[216:219], v[18:21]
	v_mfma_f32_16x16x32_bf16 v[110:113], v[138:141], v[196:199], v[110:113]
	v_mfma_f32_16x16x32_bf16 v[78:81], v[138:141], v[200:203], v[78:81]
	v_mfma_f32_16x16x32_bf16 v[46:49], v[138:141], v[204:207], v[46:49]
	v_mfma_f32_16x16x32_bf16 v[14:17], v[138:141], v[216:219], v[14:17]
	v_mfma_f32_16x16x32_bf16 v[106:109], v[142:145], v[196:199], v[106:109]
	v_mfma_f32_16x16x32_bf16 v[74:77], v[142:145], v[200:203], v[74:77]
	v_mfma_f32_16x16x32_bf16 v[42:45], v[142:145], v[204:207], v[42:45]
	v_mfma_f32_16x16x32_bf16 v[10:13], v[142:145], v[216:219], v[10:13]
	v_mfma_f32_16x16x32_bf16 v[102:105], v[150:153], v[196:199], v[102:105]
	v_mfma_f32_16x16x32_bf16 v[70:73], v[150:153], v[200:203], v[70:73]
	v_mfma_f32_16x16x32_bf16 v[38:41], v[150:153], v[204:207], v[38:41]
	v_mfma_f32_16x16x32_bf16 v[6:9], v[150:153], v[216:219], v[6:9]
	v_mfma_f32_16x16x32_bf16 v[98:101], v[154:157], v[196:199], v[98:101]
	v_mfma_f32_16x16x32_bf16 v[66:69], v[154:157], v[200:203], v[66:69]
	v_mfma_f32_16x16x32_bf16 v[34:37], v[154:157], v[204:207], v[34:37]
	v_mfma_f32_16x16x32_bf16 v[2:5], v[154:157], v[216:219], v[2:5]
	v_mfma_f32_16x16x32_bf16 v[166:169], v[158:161], v[226:229], v[166:169]
	v_mfma_f32_16x16x32_bf16 v[94:97], v[158:161], v[230:233], v[94:97]
	v_mfma_f32_16x16x32_bf16 v[62:65], v[158:161], v[234:237], v[62:65]
	v_mfma_f32_16x16x32_bf16 v[30:33], v[158:161], v[238:241], v[30:33]
	v_mfma_f32_16x16x32_bf16 v[146:149], v[162:165], v[226:229], v[146:149]
	v_mfma_f32_16x16x32_bf16 v[90:93], v[162:165], v[230:233], v[90:93]
	v_mfma_f32_16x16x32_bf16 v[58:61], v[162:165], v[234:237], v[58:61]
	v_mfma_f32_16x16x32_bf16 v[26:29], v[162:165], v[238:241], v[26:29]
	v_mfma_f32_16x16x32_bf16 v[134:137], v[170:173], v[226:229], v[134:137]
	v_mfma_f32_16x16x32_bf16 v[86:89], v[170:173], v[230:233], v[86:89]
	v_mfma_f32_16x16x32_bf16 v[54:57], v[170:173], v[234:237], v[54:57]
	v_mfma_f32_16x16x32_bf16 v[22:25], v[170:173], v[238:241], v[22:25]
	v_mfma_f32_16x16x32_bf16 v[114:117], v[174:177], v[226:229], v[114:117]
	v_mfma_f32_16x16x32_bf16 v[82:85], v[174:177], v[230:233], v[82:85]
	v_mfma_f32_16x16x32_bf16 v[50:53], v[174:177], v[234:237], v[50:53]
	v_mfma_f32_16x16x32_bf16 v[18:21], v[174:177], v[238:241], v[18:21]
	v_mfma_f32_16x16x32_bf16 v[110:113], v[180:183], v[226:229], v[110:113]
	v_mfma_f32_16x16x32_bf16 v[78:81], v[180:183], v[230:233], v[78:81]
	v_mfma_f32_16x16x32_bf16 v[46:49], v[180:183], v[234:237], v[46:49]
	v_mfma_f32_16x16x32_bf16 v[14:17], v[180:183], v[238:241], v[14:17]
	v_mfma_f32_16x16x32_bf16 v[106:109], v[184:187], v[226:229], v[106:109]
	v_mfma_f32_16x16x32_bf16 v[74:77], v[184:187], v[230:233], v[74:77]
	v_mfma_f32_16x16x32_bf16 v[42:45], v[184:187], v[234:237], v[42:45]
	v_mfma_f32_16x16x32_bf16 v[10:13], v[184:187], v[238:241], v[10:13]
	v_mfma_f32_16x16x32_bf16 v[102:105], v[188:191], v[226:229], v[102:105]
	v_mfma_f32_16x16x32_bf16 v[70:73], v[188:191], v[230:233], v[70:73]
	v_mfma_f32_16x16x32_bf16 v[38:41], v[188:191], v[234:237], v[38:41]
	v_mfma_f32_16x16x32_bf16 v[6:9], v[188:191], v[238:241], v[6:9]
	v_mfma_f32_16x16x32_bf16 v[98:101], v[192:195], v[226:229], v[98:101]
	v_mfma_f32_16x16x32_bf16 v[66:69], v[192:195], v[230:233], v[66:69]
	v_mfma_f32_16x16x32_bf16 v[34:37], v[192:195], v[234:237], v[34:37]
	v_mfma_f32_16x16x32_bf16 v[2:5], v[192:195], v[238:241], v[2:5]
	s_branch .LBB0_663

.Lg3_ein_loop:
	s_waitcnt vmcnt(0)
	ds_read_b128 v[226:229], v122
	ds_read_b128 v[230:233], v122 offset:2048
	ds_read_b128 v[234:237], v122 offset:4096
	ds_read_b128 v[238:241], v122 offset:6144
	ds_read_b128 v[242:245], v124
	ds_read_b128 v[246:249], v124 offset:2048
	s_barrier
	ds_read_b128 v[110:113], v126
	ds_read_b128 v[138:141], v126 offset:2048
	ds_read_b128 v[142:145], v126 offset:4096
	ds_read_b128 v[146:149], v126 offset:6144
	ds_read_b128 v[154:157], v126 offset:8192
	ds_read_b128 v[158:161], v126 offset:10240
	ds_read_b128 v[166:169], v126 offset:12288
	ds_read_b128 v[170:173], v126 offset:14336
	s_waitcnt lgkmcnt(7)
	v_mfma_f32_16x16x32_bf16 v[174:177], v[110:113], v[226:229], v[174:177]
	v_mfma_f32_16x16x32_bf16 v[94:97], v[110:113], v[230:233], v[94:97]
	v_mfma_f32_16x16x32_bf16 v[62:65], v[110:113], v[234:237], v[62:65]
	v_mfma_f32_16x16x32_bf16 v[30:33], v[110:113], v[238:241], v[30:33]
	s_waitcnt lgkmcnt(6)
	v_mfma_f32_16x16x32_bf16 v[162:165], v[138:141], v[226:229], v[162:165]
	v_mfma_f32_16x16x32_bf16 v[90:93], v[138:141], v[230:233], v[90:93]
	v_mfma_f32_16x16x32_bf16 v[58:61], v[138:141], v[234:237], v[58:61]
	v_mfma_f32_16x16x32_bf16 v[26:29], v[138:141], v[238:241], v[26:29]
	ds_read_b128 v[138:141], v124 offset:4096
	ds_read_b128 v[110:113], v124 offset:6144
	ds_read_b128 v[180:183], v128
	ds_read_b128 v[184:187], v128 offset:2048
	ds_read_b128 v[188:191], v128 offset:4096
	ds_read_b128 v[192:195], v128 offset:6144
	ds_read_b128 v[196:199], v128 offset:8192
	ds_read_b128 v[200:203], v128 offset:10240
	ds_read_b128 v[204:207], v128 offset:12288
	ds_read_b128 v[216:219], v128 offset:14336
	s_waitcnt lgkmcnt(8)
	s_mov_b32 m0, s46
	s_nop 0
	global_load_lds_dwordx4 v0, s[50:51]
	s_add_u32 m0, s46, 1024
	s_nop 0
	global_load_lds_dwordx4 v114, s[50:51]
	s_add_u32 m0, s46, 2048
	s_nop 0
	global_load_lds_dwordx4 v0, s[52:53]
	s_add_u32 m0, s46, 3072
	s_nop 0
	global_load_lds_dwordx4 v114, s[52:53]
	s_add_u32 m0, s46, 4096
	s_nop 0
	global_load_lds_dwordx4 v0, s[54:55]
	s_add_u32 m0, s46, 5120
	s_nop 0
	global_load_lds_dwordx4 v114, s[54:55]
	s_add_u32 m0, s46, 6144
	s_nop 0
	global_load_lds_dwordx4 v0, s[56:57]
	s_add_u32 m0, s46, 7168
	s_nop 0
	global_load_lds_dwordx4 v114, s[56:57]
	s_add_u32 s50, s50, 0x80
	s_addc_u32 s51, s51, 0
	s_add_u32 s52, s52, 0x80
	s_addc_u32 s53, s53, 0
	s_add_u32 s54, s54, 0x80
	s_addc_u32 s55, s55, 0
	s_add_u32 s56, s56, 0x80
	s_addc_u32 s57, s57, 0
	s_waitcnt lgkmcnt(0)
	s_barrier
	s_mov_b32 m0, s47
	s_nop 0
	global_load_lds_dwordx4 v115, s[58:59]
	s_add_u32 m0, s47, 1024
	s_nop 0
	global_load_lds_dwordx4 v116, s[58:59]
	s_add_u32 m0, s47, 2048
	s_nop 0
	global_load_lds_dwordx4 v115, s[60:61]
	s_add_u32 m0, s47, 3072
	s_nop 0
	global_load_lds_dwordx4 v116, s[60:61]
	s_add_u32 s58, s58, 0x80
	s_addc_u32 s59, s59, 0
	s_add_u32 s60, s60, 0x80
	s_addc_u32 s61, s61, 0
	v_mfma_f32_16x16x32_bf16 v[150:153], v[142:145], v[226:229], v[150:153]
	v_mfma_f32_16x16x32_bf16 v[86:89], v[142:145], v[230:233], v[86:89]
	v_mfma_f32_16x16x32_bf16 v[54:57], v[142:145], v[234:237], v[54:57]
	v_mfma_f32_16x16x32_bf16 v[22:25], v[142:145], v[238:241], v[22:25]
	v_mfma_f32_16x16x32_bf16 v[130:133], v[146:149], v[226:229], v[130:133]
	v_mfma_f32_16x16x32_bf16 v[82:85], v[146:149], v[230:233], v[82:85]
	v_mfma_f32_16x16x32_bf16 v[50:53], v[146:149], v[234:237], v[50:53]
	v_mfma_f32_16x16x32_bf16 v[18:21], v[146:149], v[238:241], v[18:21]
	v_mfma_f32_16x16x32_bf16 v[118:121], v[154:157], v[226:229], v[118:121]
	v_mfma_f32_16x16x32_bf16 v[78:81], v[154:157], v[230:233], v[78:81]
	v_mfma_f32_16x16x32_bf16 v[46:49], v[154:157], v[234:237], v[46:49]
	v_mfma_f32_16x16x32_bf16 v[14:17], v[154:157], v[238:241], v[14:17]
	v_mfma_f32_16x16x32_bf16 v[106:109], v[158:161], v[226:229], v[106:109]
	v_mfma_f32_16x16x32_bf16 v[74:77], v[158:161], v[230:233], v[74:77]
	v_mfma_f32_16x16x32_bf16 v[42:45], v[158:161], v[234:237], v[42:45]
	v_mfma_f32_16x16x32_bf16 v[10:13], v[158:161], v[238:241], v[10:13]
	v_mfma_f32_16x16x32_bf16 v[102:105], v[166:169], v[226:229], v[102:105]
	v_mfma_f32_16x16x32_bf16 v[70:73], v[166:169], v[230:233], v[70:73]
	v_mfma_f32_16x16x32_bf16 v[38:41], v[166:169], v[234:237], v[38:41]
	v_mfma_f32_16x16x32_bf16 v[6:9], v[166:169], v[238:241], v[6:9]
	v_mfma_f32_16x16x32_bf16 v[98:101], v[170:173], v[226:229], v[98:101]
	v_mfma_f32_16x16x32_bf16 v[66:69], v[170:173], v[230:233], v[66:69]
	v_mfma_f32_16x16x32_bf16 v[34:37], v[170:173], v[234:237], v[34:37]
	v_mfma_f32_16x16x32_bf16 v[2:5], v[170:173], v[238:241], v[2:5]
	v_mfma_f32_16x16x32_bf16 v[174:177], v[180:183], v[242:245], v[174:177]
	v_mfma_f32_16x16x32_bf16 v[94:97], v[180:183], v[246:249], v[94:97]
	v_mfma_f32_16x16x32_bf16 v[62:65], v[180:183], v[138:141], v[62:65]
	v_mfma_f32_16x16x32_bf16 v[30:33], v[180:183], v[110:113], v[30:33]
	v_mfma_f32_16x16x32_bf16 v[162:165], v[184:187], v[242:245], v[162:165]
	v_mfma_f32_16x16x32_bf16 v[90:93], v[184:187], v[246:249], v[90:93]
	v_mfma_f32_16x16x32_bf16 v[58:61], v[184:187], v[138:141], v[58:61]
	v_mfma_f32_16x16x32_bf16 v[26:29], v[184:187], v[110:113], v[26:29]
	v_mfma_f32_16x16x32_bf16 v[150:153], v[188:191], v[242:245], v[150:153]
	v_mfma_f32_16x16x32_bf16 v[86:89], v[188:191], v[246:249], v[86:89]
	v_mfma_f32_16x16x32_bf16 v[54:57], v[188:191], v[138:141], v[54:57]
	v_mfma_f32_16x16x32_bf16 v[22:25], v[188:191], v[110:113], v[22:25]
	v_mfma_f32_16x16x32_bf16 v[130:133], v[192:195], v[242:245], v[130:133]
	v_mfma_f32_16x16x32_bf16 v[82:85], v[192:195], v[246:249], v[82:85]
	v_mfma_f32_16x16x32_bf16 v[50:53], v[192:195], v[138:141], v[50:53]
	v_mfma_f32_16x16x32_bf16 v[18:21], v[192:195], v[110:113], v[18:21]
	v_mfma_f32_16x16x32_bf16 v[118:121], v[196:199], v[242:245], v[118:121]
	v_mfma_f32_16x16x32_bf16 v[78:81], v[196:199], v[246:249], v[78:81]
	v_mfma_f32_16x16x32_bf16 v[46:49], v[196:199], v[138:141], v[46:49]
	v_mfma_f32_16x16x32_bf16 v[14:17], v[196:199], v[110:113], v[14:17]
	v_mfma_f32_16x16x32_bf16 v[106:109], v[200:203], v[242:245], v[106:109]
	v_mfma_f32_16x16x32_bf16 v[74:77], v[200:203], v[246:249], v[74:77]
	v_mfma_f32_16x16x32_bf16 v[42:45], v[200:203], v[138:141], v[42:45]
	v_mfma_f32_16x16x32_bf16 v[10:13], v[200:203], v[110:113], v[10:13]
	v_mfma_f32_16x16x32_bf16 v[102:105], v[204:207], v[242:245], v[102:105]
	v_mfma_f32_16x16x32_bf16 v[70:73], v[204:207], v[246:249], v[70:73]
	v_mfma_f32_16x16x32_bf16 v[38:41], v[204:207], v[138:141], v[38:41]
	v_mfma_f32_16x16x32_bf16 v[6:9], v[204:207], v[110:113], v[6:9]
	v_mfma_f32_16x16x32_bf16 v[98:101], v[216:219], v[242:245], v[98:101]
	v_mfma_f32_16x16x32_bf16 v[66:69], v[216:219], v[246:249], v[66:69]
	v_mfma_f32_16x16x32_bf16 v[34:37], v[216:219], v[138:141], v[34:37]
	v_mfma_f32_16x16x32_bf16 v[2:5], v[216:219], v[110:113], v[2:5]
	s_sub_u32 s49, s49, 1
	s_cmp_lg_u32 s49, 0
	s_cbranch_scc1 .Lg3_ein_loop
	s_waitcnt vmcnt(0)
	ds_read_b128 v[226:229], v122
	ds_read_b128 v[230:233], v122 offset:2048
	ds_read_b128 v[234:237], v122 offset:4096
	ds_read_b128 v[238:241], v122 offset:6144
	ds_read_b128 v[242:245], v124
	ds_read_b128 v[246:249], v124 offset:2048
	s_barrier
	ds_read_b128 v[110:113], v126
	ds_read_b128 v[138:141], v126 offset:2048
	ds_read_b128 v[142:145], v126 offset:4096
	ds_read_b128 v[146:149], v126 offset:6144
	ds_read_b128 v[154:157], v126 offset:8192
	ds_read_b128 v[158:161], v126 offset:10240
	ds_read_b128 v[166:169], v126 offset:12288
	ds_read_b128 v[170:173], v126 offset:14336
	s_waitcnt lgkmcnt(7)
	v_mfma_f32_16x16x32_bf16 v[174:177], v[110:113], v[226:229], v[174:177]
	v_mfma_f32_16x16x32_bf16 v[94:97], v[110:113], v[230:233], v[94:97]
	v_mfma_f32_16x16x32_bf16 v[62:65], v[110:113], v[234:237], v[62:65]
	v_mfma_f32_16x16x32_bf16 v[30:33], v[110:113], v[238:241], v[30:33]
	s_waitcnt lgkmcnt(6)
	v_mfma_f32_16x16x32_bf16 v[162:165], v[138:141], v[226:229], v[162:165]
	v_mfma_f32_16x16x32_bf16 v[90:93], v[138:141], v[230:233], v[90:93]
	v_mfma_f32_16x16x32_bf16 v[58:61], v[138:141], v[234:237], v[58:61]
	v_mfma_f32_16x16x32_bf16 v[26:29], v[138:141], v[238:241], v[26:29]
	ds_read_b128 v[138:141], v124 offset:4096
	ds_read_b128 v[110:113], v124 offset:6144
	ds_read_b128 v[180:183], v128
	ds_read_b128 v[184:187], v128 offset:2048
	ds_read_b128 v[188:191], v128 offset:4096
	ds_read_b128 v[192:195], v128 offset:6144
	ds_read_b128 v[196:199], v128 offset:8192
	ds_read_b128 v[200:203], v128 offset:10240
	ds_read_b128 v[204:207], v128 offset:12288
	ds_read_b128 v[216:219], v128 offset:14336
	s_waitcnt lgkmcnt(8)
	s_waitcnt lgkmcnt(0)
	s_barrier
	v_mfma_f32_16x16x32_bf16 v[150:153], v[142:145], v[226:229], v[150:153]
	v_mfma_f32_16x16x32_bf16 v[86:89], v[142:145], v[230:233], v[86:89]
	v_mfma_f32_16x16x32_bf16 v[54:57], v[142:145], v[234:237], v[54:57]
	v_mfma_f32_16x16x32_bf16 v[22:25], v[142:145], v[238:241], v[22:25]
	v_mfma_f32_16x16x32_bf16 v[130:133], v[146:149], v[226:229], v[130:133]
	v_mfma_f32_16x16x32_bf16 v[82:85], v[146:149], v[230:233], v[82:85]
	v_mfma_f32_16x16x32_bf16 v[50:53], v[146:149], v[234:237], v[50:53]
	v_mfma_f32_16x16x32_bf16 v[18:21], v[146:149], v[238:241], v[18:21]
	v_mfma_f32_16x16x32_bf16 v[118:121], v[154:157], v[226:229], v[118:121]
	v_mfma_f32_16x16x32_bf16 v[78:81], v[154:157], v[230:233], v[78:81]
	v_mfma_f32_16x16x32_bf16 v[46:49], v[154:157], v[234:237], v[46:49]
	v_mfma_f32_16x16x32_bf16 v[14:17], v[154:157], v[238:241], v[14:17]
	v_mfma_f32_16x16x32_bf16 v[106:109], v[158:161], v[226:229], v[106:109]
	v_mfma_f32_16x16x32_bf16 v[74:77], v[158:161], v[230:233], v[74:77]
	v_mfma_f32_16x16x32_bf16 v[42:45], v[158:161], v[234:237], v[42:45]
	v_mfma_f32_16x16x32_bf16 v[10:13], v[158:161], v[238:241], v[10:13]
	v_mfma_f32_16x16x32_bf16 v[102:105], v[166:169], v[226:229], v[102:105]
	v_mfma_f32_16x16x32_bf16 v[70:73], v[166:169], v[230:233], v[70:73]
	v_mfma_f32_16x16x32_bf16 v[38:41], v[166:169], v[234:237], v[38:41]
	v_mfma_f32_16x16x32_bf16 v[6:9], v[166:169], v[238:241], v[6:9]
	v_mfma_f32_16x16x32_bf16 v[98:101], v[170:173], v[226:229], v[98:101]
	v_mfma_f32_16x16x32_bf16 v[66:69], v[170:173], v[230:233], v[66:69]
	v_mfma_f32_16x16x32_bf16 v[34:37], v[170:173], v[234:237], v[34:37]
	v_mfma_f32_16x16x32_bf16 v[2:5], v[170:173], v[238:241], v[2:5]
	v_mfma_f32_16x16x32_bf16 v[174:177], v[180:183], v[242:245], v[174:177]
	v_mfma_f32_16x16x32_bf16 v[94:97], v[180:183], v[246:249], v[94:97]
	v_mfma_f32_16x16x32_bf16 v[62:65], v[180:183], v[138:141], v[62:65]
	v_mfma_f32_16x16x32_bf16 v[30:33], v[180:183], v[110:113], v[30:33]
	v_mfma_f32_16x16x32_bf16 v[162:165], v[184:187], v[242:245], v[162:165]
	v_mfma_f32_16x16x32_bf16 v[90:93], v[184:187], v[246:249], v[90:93]
	v_mfma_f32_16x16x32_bf16 v[58:61], v[184:187], v[138:141], v[58:61]
	v_mfma_f32_16x16x32_bf16 v[26:29], v[184:187], v[110:113], v[26:29]
	v_mfma_f32_16x16x32_bf16 v[150:153], v[188:191], v[242:245], v[150:153]
	v_mfma_f32_16x16x32_bf16 v[86:89], v[188:191], v[246:249], v[86:89]
	v_mfma_f32_16x16x32_bf16 v[54:57], v[188:191], v[138:141], v[54:57]
	v_mfma_f32_16x16x32_bf16 v[22:25], v[188:191], v[110:113], v[22:25]
	v_mfma_f32_16x16x32_bf16 v[130:133], v[192:195], v[242:245], v[130:133]
	v_mfma_f32_16x16x32_bf16 v[82:85], v[192:195], v[246:249], v[82:85]
	v_mfma_f32_16x16x32_bf16 v[50:53], v[192:195], v[138:141], v[50:53]
	v_mfma_f32_16x16x32_bf16 v[18:21], v[192:195], v[110:113], v[18:21]
	v_mfma_f32_16x16x32_bf16 v[118:121], v[196:199], v[242:245], v[118:121]
	v_mfma_f32_16x16x32_bf16 v[78:81], v[196:199], v[246:249], v[78:81]
	v_mfma_f32_16x16x32_bf16 v[46:49], v[196:199], v[138:141], v[46:49]
	v_mfma_f32_16x16x32_bf16 v[14:17], v[196:199], v[110:113], v[14:17]
	v_mfma_f32_16x16x32_bf16 v[106:109], v[200:203], v[242:245], v[106:109]
	v_mfma_f32_16x16x32_bf16 v[74:77], v[200:203], v[246:249], v[74:77]
	v_mfma_f32_16x16x32_bf16 v[42:45], v[200:203], v[138:141], v[42:45]
	v_mfma_f32_16x16x32_bf16 v[10:13], v[200:203], v[110:113], v[10:13]
	v_mfma_f32_16x16x32_bf16 v[102:105], v[204:207], v[242:245], v[102:105]
	v_mfma_f32_16x16x32_bf16 v[70:73], v[204:207], v[246:249], v[70:73]
	v_mfma_f32_16x16x32_bf16 v[38:41], v[204:207], v[138:141], v[38:41]
	v_mfma_f32_16x16x32_bf16 v[6:9], v[204:207], v[110:113], v[6:9]
	v_mfma_f32_16x16x32_bf16 v[98:101], v[216:219], v[242:245], v[98:101]
	v_mfma_f32_16x16x32_bf16 v[66:69], v[216:219], v[246:249], v[66:69]
	v_mfma_f32_16x16x32_bf16 v[34:37], v[216:219], v[138:141], v[34:37]
	v_mfma_f32_16x16x32_bf16 v[2:5], v[216:219], v[110:113], v[2:5]
	s_branch .LBB0_844

.Lg3_oev_loop:
	s_waitcnt vmcnt(0)
	ds_read_b128 v[196:199], v243
	ds_read_b128 v[200:203], v243 offset:2048
	ds_read_b128 v[204:207], v243 offset:4096
	ds_read_b128 v[216:219], v243 offset:6144
	ds_read_b128 v[226:229], v244
	ds_read_b128 v[230:233], v244 offset:2048
	ds_read_b128 v[234:237], v244 offset:4096
	ds_read_b128 v[238:241], v244 offset:6144
	s_barrier
	ds_read_b128 v[118:121], v245
	ds_read_b128 v[122:125], v245 offset:2048
	ds_read_b128 v[126:129], v245 offset:4096
	ds_read_b128 v[134:137], v245 offset:6144
	ds_read_b128 v[138:141], v245 offset:8192
	ds_read_b128 v[142:145], v245 offset:10240
	ds_read_b128 v[150:153], v245 offset:12288
	ds_read_b128 v[154:157], v245 offset:14336
	ds_read_b128 v[158:161], v246
	ds_read_b128 v[162:165], v246 offset:2048
	ds_read_b128 v[170:173], v246 offset:4096
	ds_read_b128 v[174:177], v246 offset:6144
	ds_read_b128 v[180:183], v246 offset:8192
	ds_read_b128 v[184:187], v246 offset:10240
	ds_read_b128 v[188:191], v246 offset:12288
	ds_read_b128 v[192:195], v246 offset:14336
	s_waitcnt lgkmcnt(8)
	s_mov_b32 m0, s46
	s_nop 0
	global_load_lds_dwordx4 v0, s[50:51]
	s_add_u32 m0, s46, 1024
	s_nop 0
	global_load_lds_dwordx4 v208, s[50:51]
	s_add_u32 m0, s46, 2048
	s_nop 0
	global_load_lds_dwordx4 v0, s[52:53]
	s_add_u32 m0, s46, 3072
	s_nop 0
	global_load_lds_dwordx4 v208, s[52:53]
	s_add_u32 m0, s46, 4096
	s_nop 0
	global_load_lds_dwordx4 v0, s[54:55]
	s_add_u32 m0, s46, 5120
	s_nop 0
	global_load_lds_dwordx4 v208, s[54:55]
	s_add_u32 m0, s46, 6144
	s_nop 0
	global_load_lds_dwordx4 v0, s[56:57]
	s_add_u32 m0, s46, 7168
	s_nop 0
	global_load_lds_dwordx4 v208, s[56:57]
	s_add_u32 s50, s50, 0x80
	s_addc_u32 s51, s51, 0
	s_add_u32 s52, s52, 0x80
	s_addc_u32 s53, s53, 0
	s_add_u32 s54, s54, 0x80
	s_addc_u32 s55, s55, 0
	s_add_u32 s56, s56, 0x80
	s_addc_u32 s57, s57, 0
	s_waitcnt lgkmcnt(0)
	s_barrier
	s_mov_b32 m0, s47
	s_nop 0
	global_load_lds_dwordx4 v209, s[58:59]
	s_add_u32 m0, s47, 1024
	s_nop 0
	global_load_lds_dwordx4 v242, s[58:59]
	s_add_u32 m0, s47, 2048
	s_nop 0
	global_load_lds_dwordx4 v209, s[60:61]
	s_add_u32 m0, s47, 3072
	s_nop 0
	global_load_lds_dwordx4 v242, s[60:61]
	s_add_u32 s58, s58, 0x80
	s_addc_u32 s59, s59, 0
	s_add_u32 s60, s60, 0x80
	s_addc_u32 s61, s61, 0
	v_mfma_f32_16x16x32_bf16 v[166:169], v[118:121], v[196:199], v[166:169]
	v_mfma_f32_16x16x32_bf16 v[94:97], v[118:121], v[200:203], v[94:97]
	v_mfma_f32_16x16x32_bf16 v[62:65], v[118:121], v[204:207], v[62:65]
	v_mfma_f32_16x16x32_bf16 v[30:33], v[118:121], v[216:219], v[30:33]
	v_mfma_f32_16x16x32_bf16 v[146:149], v[122:125], v[196:199], v[146:149]
	v_mfma_f32_16x16x32_bf16 v[90:93], v[122:125], v[200:203], v[90:93]
	v_mfma_f32_16x16x32_bf16 v[58:61], v[122:125], v[204:207], v[58:61]
	v_mfma_f32_16x16x32_bf16 v[26:29], v[122:125], v[216:219], v[26:29]
	v_mfma_f32_16x16x32_bf16 v[130:133], v[126:129], v[196:199], v[130:133]
	v_mfma_f32_16x16x32_bf16 v[86:89], v[126:129], v[200:203], v[86:89]
	v_mfma_f32_16x16x32_bf16 v[54:57], v[126:129], v[204:207], v[54:57]
	v_mfma_f32_16x16x32_bf16 v[22:25], v[126:129], v[216:219], v[22:25]
	v_mfma_f32_16x16x32_bf16 v[114:117], v[134:137], v[196:199], v[114:117]
	v_mfma_f32_16x16x32_bf16 v[82:85], v[134:137], v[200:203], v[82:85]
	v_mfma_f32_16x16x32_bf16 v[50:53], v[134:137], v[204:207], v[50:53]
	v_mfma_f32_16x16x32_bf16 v[18:21], v[134:137], v[216:219], v[18:21]
	v_mfma_f32_16x16x32_bf16 v[110:113], v[138:141], v[196:199], v[110:113]
	v_mfma_f32_16x16x32_bf16 v[78:81], v[138:141], v[200:203], v[78:81]
	v_mfma_f32_16x16x32_bf16 v[46:49], v[138:141], v[204:207], v[46:49]
	v_mfma_f32_16x16x32_bf16 v[14:17], v[138:141], v[216:219], v[14:17]
	v_mfma_f32_16x16x32_bf16 v[106:109], v[142:145], v[196:199], v[106:109]
	v_mfma_f32_16x16x32_bf16 v[74:77], v[142:145], v[200:203], v[74:77]
	v_mfma_f32_16x16x32_bf16 v[42:45], v[142:145], v[204:207], v[42:45]
	v_mfma_f32_16x16x32_bf16 v[10:13], v[142:145], v[216:219], v[10:13]
	v_mfma_f32_16x16x32_bf16 v[102:105], v[150:153], v[196:199], v[102:105]
	v_mfma_f32_16x16x32_bf16 v[70:73], v[150:153], v[200:203], v[70:73]
	v_mfma_f32_16x16x32_bf16 v[38:41], v[150:153], v[204:207], v[38:41]
	v_mfma_f32_16x16x32_bf16 v[6:9], v[150:153], v[216:219], v[6:9]
	v_mfma_f32_16x16x32_bf16 v[98:101], v[154:157], v[196:199], v[98:101]
	v_mfma_f32_16x16x32_bf16 v[66:69], v[154:157], v[200:203], v[66:69]
	v_mfma_f32_16x16x32_bf16 v[34:37], v[154:157], v[204:207], v[34:37]
	v_mfma_f32_16x16x32_bf16 v[2:5], v[154:157], v[216:219], v[2:5]
	v_mfma_f32_16x16x32_bf16 v[166:169], v[158:161], v[226:229], v[166:169]
	v_mfma_f32_16x16x32_bf16 v[94:97], v[158:161], v[230:233], v[94:97]
	v_mfma_f32_16x16x32_bf16 v[62:65], v[158:161], v[234:237], v[62:65]
	v_mfma_f32_16x16x32_bf16 v[30:33], v[158:161], v[238:241], v[30:33]
	v_mfma_f32_16x16x32_bf16 v[146:149], v[162:165], v[226:229], v[146:149]
	v_mfma_f32_16x16x32_bf16 v[90:93], v[162:165], v[230:233], v[90:93]
	v_mfma_f32_16x16x32_bf16 v[58:61], v[162:165], v[234:237], v[58:61]
	v_mfma_f32_16x16x32_bf16 v[26:29], v[162:165], v[238:241], v[26:29]
	v_mfma_f32_16x16x32_bf16 v[130:133], v[170:173], v[226:229], v[130:133]
	v_mfma_f32_16x16x32_bf16 v[86:89], v[170:173], v[230:233], v[86:89]
	v_mfma_f32_16x16x32_bf16 v[54:57], v[170:173], v[234:237], v[54:57]
	v_mfma_f32_16x16x32_bf16 v[22:25], v[170:173], v[238:241], v[22:25]
	v_mfma_f32_16x16x32_bf16 v[114:117], v[174:177], v[226:229], v[114:117]
	v_mfma_f32_16x16x32_bf16 v[82:85], v[174:177], v[230:233], v[82:85]
	v_mfma_f32_16x16x32_bf16 v[50:53], v[174:177], v[234:237], v[50:53]
	v_mfma_f32_16x16x32_bf16 v[18:21], v[174:177], v[238:241], v[18:21]
	v_mfma_f32_16x16x32_bf16 v[110:113], v[180:183], v[226:229], v[110:113]
	v_mfma_f32_16x16x32_bf16 v[78:81], v[180:183], v[230:233], v[78:81]
	v_mfma_f32_16x16x32_bf16 v[46:49], v[180:183], v[234:237], v[46:49]
	v_mfma_f32_16x16x32_bf16 v[14:17], v[180:183], v[238:241], v[14:17]
	v_mfma_f32_16x16x32_bf16 v[106:109], v[184:187], v[226:229], v[106:109]
	v_mfma_f32_16x16x32_bf16 v[74:77], v[184:187], v[230:233], v[74:77]
	v_mfma_f32_16x16x32_bf16 v[42:45], v[184:187], v[234:237], v[42:45]
	v_mfma_f32_16x16x32_bf16 v[10:13], v[184:187], v[238:241], v[10:13]
	v_mfma_f32_16x16x32_bf16 v[102:105], v[188:191], v[226:229], v[102:105]
	v_mfma_f32_16x16x32_bf16 v[70:73], v[188:191], v[230:233], v[70:73]
	v_mfma_f32_16x16x32_bf16 v[38:41], v[188:191], v[234:237], v[38:41]
	v_mfma_f32_16x16x32_bf16 v[6:9], v[188:191], v[238:241], v[6:9]
	v_mfma_f32_16x16x32_bf16 v[98:101], v[192:195], v[226:229], v[98:101]
	v_mfma_f32_16x16x32_bf16 v[66:69], v[192:195], v[230:233], v[66:69]
	v_mfma_f32_16x16x32_bf16 v[34:37], v[192:195], v[234:237], v[34:37]
	v_mfma_f32_16x16x32_bf16 v[2:5], v[192:195], v[238:241], v[2:5]
	s_sub_u32 s49, s49, 1
	s_cmp_lg_u32 s49, 0
	s_cbranch_scc1 .Lg3_oev_loop
	s_waitcnt vmcnt(0)
	ds_read_b128 v[196:199], v243
	ds_read_b128 v[200:203], v243 offset:2048
	ds_read_b128 v[204:207], v243 offset:4096
	ds_read_b128 v[216:219], v243 offset:6144
	ds_read_b128 v[226:229], v244
	ds_read_b128 v[230:233], v244 offset:2048
	ds_read_b128 v[234:237], v244 offset:4096
	ds_read_b128 v[238:241], v244 offset:6144
	s_barrier
	ds_read_b128 v[118:121], v245
	ds_read_b128 v[122:125], v245 offset:2048
	ds_read_b128 v[126:129], v245 offset:4096
	ds_read_b128 v[134:137], v245 offset:6144
	ds_read_b128 v[138:141], v245 offset:8192
	ds_read_b128 v[142:145], v245 offset:10240
	ds_read_b128 v[150:153], v245 offset:12288
	ds_read_b128 v[154:157], v245 offset:14336
	ds_read_b128 v[158:161], v246
	ds_read_b128 v[162:165], v246 offset:2048
	ds_read_b128 v[170:173], v246 offset:4096
	ds_read_b128 v[174:177], v246 offset:6144
	ds_read_b128 v[180:183], v246 offset:8192
	ds_read_b128 v[184:187], v246 offset:10240
	ds_read_b128 v[188:191], v246 offset:12288
	ds_read_b128 v[192:195], v246 offset:14336
	s_waitcnt lgkmcnt(8)
	s_waitcnt lgkmcnt(0)
	s_barrier
	v_mfma_f32_16x16x32_bf16 v[166:169], v[118:121], v[196:199], v[166:169]
	v_mfma_f32_16x16x32_bf16 v[94:97], v[118:121], v[200:203], v[94:97]
	v_mfma_f32_16x16x32_bf16 v[62:65], v[118:121], v[204:207], v[62:65]
	v_mfma_f32_16x16x32_bf16 v[30:33], v[118:121], v[216:219], v[30:33]
	v_mfma_f32_16x16x32_bf16 v[146:149], v[122:125], v[196:199], v[146:149]
	v_mfma_f32_16x16x32_bf16 v[90:93], v[122:125], v[200:203], v[90:93]
	v_mfma_f32_16x16x32_bf16 v[58:61], v[122:125], v[204:207], v[58:61]
	v_mfma_f32_16x16x32_bf16 v[26:29], v[122:125], v[216:219], v[26:29]
	v_mfma_f32_16x16x32_bf16 v[130:133], v[126:129], v[196:199], v[130:133]
	v_mfma_f32_16x16x32_bf16 v[86:89], v[126:129], v[200:203], v[86:89]
	v_mfma_f32_16x16x32_bf16 v[54:57], v[126:129], v[204:207], v[54:57]
	v_mfma_f32_16x16x32_bf16 v[22:25], v[126:129], v[216:219], v[22:25]
	v_mfma_f32_16x16x32_bf16 v[114:117], v[134:137], v[196:199], v[114:117]
	v_mfma_f32_16x16x32_bf16 v[82:85], v[134:137], v[200:203], v[82:85]
	v_mfma_f32_16x16x32_bf16 v[50:53], v[134:137], v[204:207], v[50:53]
	v_mfma_f32_16x16x32_bf16 v[18:21], v[134:137], v[216:219], v[18:21]
	v_mfma_f32_16x16x32_bf16 v[110:113], v[138:141], v[196:199], v[110:113]
	v_mfma_f32_16x16x32_bf16 v[78:81], v[138:141], v[200:203], v[78:81]
	v_mfma_f32_16x16x32_bf16 v[46:49], v[138:141], v[204:207], v[46:49]
	v_mfma_f32_16x16x32_bf16 v[14:17], v[138:141], v[216:219], v[14:17]
	v_mfma_f32_16x16x32_bf16 v[106:109], v[142:145], v[196:199], v[106:109]
	v_mfma_f32_16x16x32_bf16 v[74:77], v[142:145], v[200:203], v[74:77]
	v_mfma_f32_16x16x32_bf16 v[42:45], v[142:145], v[204:207], v[42:45]
	v_mfma_f32_16x16x32_bf16 v[10:13], v[142:145], v[216:219], v[10:13]
	v_mfma_f32_16x16x32_bf16 v[102:105], v[150:153], v[196:199], v[102:105]
	v_mfma_f32_16x16x32_bf16 v[70:73], v[150:153], v[200:203], v[70:73]
	v_mfma_f32_16x16x32_bf16 v[38:41], v[150:153], v[204:207], v[38:41]
	v_mfma_f32_16x16x32_bf16 v[6:9], v[150:153], v[216:219], v[6:9]
	v_mfma_f32_16x16x32_bf16 v[98:101], v[154:157], v[196:199], v[98:101]
	v_mfma_f32_16x16x32_bf16 v[66:69], v[154:157], v[200:203], v[66:69]
	v_mfma_f32_16x16x32_bf16 v[34:37], v[154:157], v[204:207], v[34:37]
	v_mfma_f32_16x16x32_bf16 v[2:5], v[154:157], v[216:219], v[2:5]
	v_mfma_f32_16x16x32_bf16 v[166:169], v[158:161], v[226:229], v[166:169]
	v_mfma_f32_16x16x32_bf16 v[94:97], v[158:161], v[230:233], v[94:97]
	v_mfma_f32_16x16x32_bf16 v[62:65], v[158:161], v[234:237], v[62:65]
	v_mfma_f32_16x16x32_bf16 v[30:33], v[158:161], v[238:241], v[30:33]
	v_mfma_f32_16x16x32_bf16 v[146:149], v[162:165], v[226:229], v[146:149]
	v_mfma_f32_16x16x32_bf16 v[90:93], v[162:165], v[230:233], v[90:93]
	v_mfma_f32_16x16x32_bf16 v[58:61], v[162:165], v[234:237], v[58:61]
	v_mfma_f32_16x16x32_bf16 v[26:29], v[162:165], v[238:241], v[26:29]
	v_mfma_f32_16x16x32_bf16 v[130:133], v[170:173], v[226:229], v[130:133]
	v_mfma_f32_16x16x32_bf16 v[86:89], v[170:173], v[230:233], v[86:89]
	v_mfma_f32_16x16x32_bf16 v[54:57], v[170:173], v[234:237], v[54:57]
	v_mfma_f32_16x16x32_bf16 v[22:25], v[170:173], v[238:241], v[22:25]
	v_mfma_f32_16x16x32_bf16 v[114:117], v[174:177], v[226:229], v[114:117]
	v_mfma_f32_16x16x32_bf16 v[82:85], v[174:177], v[230:233], v[82:85]
	v_mfma_f32_16x16x32_bf16 v[50:53], v[174:177], v[234:237], v[50:53]
	v_mfma_f32_16x16x32_bf16 v[18:21], v[174:177], v[238:241], v[18:21]
	v_mfma_f32_16x16x32_bf16 v[110:113], v[180:183], v[226:229], v[110:113]
	v_mfma_f32_16x16x32_bf16 v[78:81], v[180:183], v[230:233], v[78:81]
	v_mfma_f32_16x16x32_bf16 v[46:49], v[180:183], v[234:237], v[46:49]
	v_mfma_f32_16x16x32_bf16 v[14:17], v[180:183], v[238:241], v[14:17]
	v_mfma_f32_16x16x32_bf16 v[106:109], v[184:187], v[226:229], v[106:109]
	v_mfma_f32_16x16x32_bf16 v[74:77], v[184:187], v[230:233], v[74:77]
	v_mfma_f32_16x16x32_bf16 v[42:45], v[184:187], v[234:237], v[42:45]
	v_mfma_f32_16x16x32_bf16 v[10:13], v[184:187], v[238:241], v[10:13]
	v_mfma_f32_16x16x32_bf16 v[102:105], v[188:191], v[226:229], v[102:105]
	v_mfma_f32_16x16x32_bf16 v[70:73], v[188:191], v[230:233], v[70:73]
	v_mfma_f32_16x16x32_bf16 v[38:41], v[188:191], v[234:237], v[38:41]
	v_mfma_f32_16x16x32_bf16 v[6:9], v[188:191], v[238:241], v[6:9]
	v_mfma_f32_16x16x32_bf16 v[98:101], v[192:195], v[226:229], v[98:101]
	v_mfma_f32_16x16x32_bf16 v[66:69], v[192:195], v[230:233], v[66:69]
	v_mfma_f32_16x16x32_bf16 v[34:37], v[192:195], v[234:237], v[34:37]
	v_mfma_f32_16x16x32_bf16 v[2:5], v[192:195], v[238:241], v[2:5]
	s_branch .LBB0_1639

.Lg3_pq_loop:
	s_waitcnt vmcnt(0)
	ds_read_b128 v[216:219], v115
	ds_read_b128 v[226:229], v115 offset:2048
	ds_read_b128 v[230:233], v115 offset:4096
	ds_read_b128 v[234:237], v115 offset:6144
	ds_read_b128 v[238:241], v116
	ds_read_b128 v[242:245], v116 offset:2048
	ds_read_b128 v[246:249], v116 offset:4096
	s_barrier
	ds_read_b128 v[10:13], v122
	ds_read_b128 v[14:17], v122 offset:2048
	ds_read_b128 v[38:41], v122 offset:4096
	ds_read_b128 v[62:65], v122 offset:6144
	ds_read_b128 v[66:69], v122 offset:8192
	ds_read_b128 v[90:93], v122 offset:10240
	ds_read_b128 v[94:97], v122 offset:12288
	ds_read_b128 v[142:145], v122 offset:14336
	s_waitcnt lgkmcnt(7)
	v_mfma_f32_16x16x32_bf16 v[174:177], v[10:13], v[216:219], v[174:177]
	v_mfma_f32_16x16x32_bf16 v[134:137], v[10:13], v[226:229], v[134:137]
	v_mfma_f32_16x16x32_bf16 v[86:89], v[10:13], v[230:233], v[86:89]
	v_mfma_f32_16x16x32_bf16 v[46:49], v[10:13], v[234:237], v[46:49]
	ds_read_b128 v[10:13], v116 offset:6144
	ds_read_b128 v[146:149], v124
	ds_read_b128 v[180:183], v124 offset:2048
	ds_read_b128 v[184:187], v124 offset:4096
	ds_read_b128 v[188:191], v124 offset:6144
	ds_read_b128 v[192:195], v124 offset:8192
	ds_read_b128 v[196:199], v124 offset:10240
	ds_read_b128 v[200:203], v124 offset:12288
	ds_read_b128 v[204:207], v124 offset:14336
	s_waitcnt lgkmcnt(8)
	s_mov_b32 m0, s46
	s_nop 0
	global_load_lds_dwordx4 v0, s[50:51]
	s_add_u32 m0, s46, 1024
	s_nop 0
	global_load_lds_dwordx4 v42, s[50:51]
	s_add_u32 m0, s46, 2048
	s_nop 0
	global_load_lds_dwordx4 v0, s[52:53]
	s_add_u32 m0, s46, 3072
	s_nop 0
	global_load_lds_dwordx4 v42, s[52:53]
	s_add_u32 m0, s46, 4096
	s_nop 0
	global_load_lds_dwordx4 v0, s[54:55]
	s_add_u32 m0, s46, 5120
	s_nop 0
	global_load_lds_dwordx4 v42, s[54:55]
	s_add_u32 m0, s46, 6144
	s_nop 0
	global_load_lds_dwordx4 v0, s[56:57]
	s_add_u32 m0, s46, 7168
	s_nop 0
	global_load_lds_dwordx4 v42, s[56:57]
	s_add_u32 s50, s50, 0x80
	s_addc_u32 s51, s51, 0
	s_add_u32 s52, s52, 0x80
	s_addc_u32 s53, s53, 0
	s_add_u32 s54, s54, 0x80
	s_addc_u32 s55, s55, 0
	s_add_u32 s56, s56, 0x80
	s_addc_u32 s57, s57, 0
	s_waitcnt lgkmcnt(0)
	s_barrier
	s_mov_b32 m0, s47
	s_nop 0
	global_load_lds_dwordx4 v43, s[58:59]
	s_add_u32 m0, s47, 1024
	s_nop 0
	global_load_lds_dwordx4 v114, s[58:59]
	s_add_u32 m0, s47, 2048
	s_nop 0
	global_load_lds_dwordx4 v43, s[60:61]
	s_add_u32 m0, s47, 3072
	s_nop 0
	global_load_lds_dwordx4 v114, s[60:61]
	s_add_u32 s58, s58, 0x80
	s_addc_u32 s59, s59, 0
	s_add_u32 s60, s60, 0x80
	s_addc_u32 s61, s61, 0
	v_mfma_f32_16x16x32_bf16 v[170:173], v[14:17], v[216:219], v[170:173]
	v_mfma_f32_16x16x32_bf16 v[130:133], v[14:17], v[226:229], v[130:133]
	v_mfma_f32_16x16x32_bf16 v[82:85], v[14:17], v[230:233], v[82:85]
	v_mfma_f32_16x16x32_bf16 v[34:37], v[14:17], v[234:237], v[34:37]
	v_mfma_f32_16x16x32_bf16 v[166:169], v[38:41], v[216:219], v[166:169]
	v_mfma_f32_16x16x32_bf16 v[126:129], v[38:41], v[226:229], v[126:129]
	v_mfma_f32_16x16x32_bf16 v[78:81], v[38:41], v[230:233], v[78:81]
	v_mfma_f32_16x16x32_bf16 v[30:33], v[38:41], v[234:237], v[30:33]
	v_mfma_f32_16x16x32_bf16 v[162:165], v[62:65], v[216:219], v[162:165]
	v_mfma_f32_16x16x32_bf16 v[118:121], v[62:65], v[226:229], v[118:121]
	v_mfma_f32_16x16x32_bf16 v[74:77], v[62:65], v[230:233], v[74:77]
	v_mfma_f32_16x16x32_bf16 v[26:29], v[62:65], v[234:237], v[26:29]
	v_mfma_f32_16x16x32_bf16 v[158:161], v[66:69], v[216:219], v[158:161]
	v_mfma_f32_16x16x32_bf16 v[110:113], v[66:69], v[226:229], v[110:113]
	v_mfma_f32_16x16x32_bf16 v[70:73], v[66:69], v[230:233], v[70:73]
	v_mfma_f32_16x16x32_bf16 v[22:25], v[66:69], v[234:237], v[22:25]
	v_mfma_f32_16x16x32_bf16 v[154:157], v[90:93], v[216:219], v[154:157]
	v_mfma_f32_16x16x32_bf16 v[106:109], v[90:93], v[226:229], v[106:109]
	v_mfma_f32_16x16x32_bf16 v[58:61], v[90:93], v[230:233], v[58:61]
	v_mfma_f32_16x16x32_bf16 v[18:21], v[90:93], v[234:237], v[18:21]
	v_mfma_f32_16x16x32_bf16 v[150:153], v[94:97], v[216:219], v[150:153]
	v_mfma_f32_16x16x32_bf16 v[102:105], v[94:97], v[226:229], v[102:105]
	v_mfma_f32_16x16x32_bf16 v[54:57], v[94:97], v[230:233], v[54:57]
	v_mfma_f32_16x16x32_bf16 v[6:9], v[94:97], v[234:237], v[6:9]
	v_mfma_f32_16x16x32_bf16 v[138:141], v[142:145], v[216:219], v[138:141]
	v_mfma_f32_16x16x32_bf16 v[98:101], v[142:145], v[226:229], v[98:101]
	v_mfma_f32_16x16x32_bf16 v[50:53], v[142:145], v[230:233], v[50:53]
	v_mfma_f32_16x16x32_bf16 v[2:5], v[142:145], v[234:237], v[2:5]
	v_mfma_f32_16x16x32_bf16 v[174:177], v[146:149], v[238:241], v[174:177]
	v_mfma_f32_16x16x32_bf16 v[134:137], v[146:149], v[242:245], v[134:137]
	v_mfma_f32_16x16x32_bf16 v[86:89], v[146:149], v[246:249], v[86:89]
	v_mfma_f32_16x16x32_bf16 v[46:49], v[146:149], v[10:13], v[46:49]
	v_mfma_f32_16x16x32_bf16 v[170:173], v[180:183], v[238:241], v[170:173]
	v_mfma_f32_16x16x32_bf16 v[130:133], v[180:183], v[242:245], v[130:133]
	v_mfma_f32_16x16x32_bf16 v[82:85], v[180:183], v[246:249], v[82:85]
	v_mfma_f32_16x16x32_bf16 v[34:37], v[180:183], v[10:13], v[34:37]
	v_mfma_f32_16x16x32_bf16 v[166:169], v[184:187], v[238:241], v[166:169]
	v_mfma_f32_16x16x32_bf16 v[126:129], v[184:187], v[242:245], v[126:129]
	v_mfma_f32_16x16x32_bf16 v[78:81], v[184:187], v[246:249], v[78:81]
	v_mfma_f32_16x16x32_bf16 v[30:33], v[184:187], v[10:13], v[30:33]
	v_mfma_f32_16x16x32_bf16 v[162:165], v[188:191], v[238:241], v[162:165]
	v_mfma_f32_16x16x32_bf16 v[118:121], v[188:191], v[242:245], v[118:121]
	v_mfma_f32_16x16x32_bf16 v[74:77], v[188:191], v[246:249], v[74:77]
	v_mfma_f32_16x16x32_bf16 v[26:29], v[188:191], v[10:13], v[26:29]
	v_mfma_f32_16x16x32_bf16 v[158:161], v[192:195], v[238:241], v[158:161]
	v_mfma_f32_16x16x32_bf16 v[110:113], v[192:195], v[242:245], v[110:113]
	v_mfma_f32_16x16x32_bf16 v[70:73], v[192:195], v[246:249], v[70:73]
	v_mfma_f32_16x16x32_bf16 v[22:25], v[192:195], v[10:13], v[22:25]
	v_mfma_f32_16x16x32_bf16 v[154:157], v[196:199], v[238:241], v[154:157]
	v_mfma_f32_16x16x32_bf16 v[106:109], v[196:199], v[242:245], v[106:109]
	v_mfma_f32_16x16x32_bf16 v[58:61], v[196:199], v[246:249], v[58:61]
	v_mfma_f32_16x16x32_bf16 v[18:21], v[196:199], v[10:13], v[18:21]
	v_mfma_f32_16x16x32_bf16 v[150:153], v[200:203], v[238:241], v[150:153]
	v_mfma_f32_16x16x32_bf16 v[102:105], v[200:203], v[242:245], v[102:105]
	v_mfma_f32_16x16x32_bf16 v[54:57], v[200:203], v[246:249], v[54:57]
	v_mfma_f32_16x16x32_bf16 v[6:9], v[200:203], v[10:13], v[6:9]
	v_mfma_f32_16x16x32_bf16 v[138:141], v[204:207], v[238:241], v[138:141]
	v_mfma_f32_16x16x32_bf16 v[98:101], v[204:207], v[242:245], v[98:101]
	v_mfma_f32_16x16x32_bf16 v[50:53], v[204:207], v[246:249], v[50:53]
	v_mfma_f32_16x16x32_bf16 v[2:5], v[204:207], v[10:13], v[2:5]
	s_sub_u32 s49, s49, 1
	s_cmp_lg_u32 s49, 0
	s_cbranch_scc1 .Lg3_pq_loop
	s_waitcnt vmcnt(0)
	ds_read_b128 v[216:219], v115
	ds_read_b128 v[226:229], v115 offset:2048
	ds_read_b128 v[230:233], v115 offset:4096
	ds_read_b128 v[234:237], v115 offset:6144
	ds_read_b128 v[238:241], v116
	ds_read_b128 v[242:245], v116 offset:2048
	ds_read_b128 v[246:249], v116 offset:4096
	s_barrier
	ds_read_b128 v[10:13], v122
	ds_read_b128 v[14:17], v122 offset:2048
	ds_read_b128 v[38:41], v122 offset:4096
	ds_read_b128 v[62:65], v122 offset:6144
	ds_read_b128 v[66:69], v122 offset:8192
	ds_read_b128 v[90:93], v122 offset:10240
	ds_read_b128 v[94:97], v122 offset:12288
	ds_read_b128 v[142:145], v122 offset:14336
	s_waitcnt lgkmcnt(7)
	v_mfma_f32_16x16x32_bf16 v[174:177], v[10:13], v[216:219], v[174:177]
	v_mfma_f32_16x16x32_bf16 v[134:137], v[10:13], v[226:229], v[134:137]
	v_mfma_f32_16x16x32_bf16 v[86:89], v[10:13], v[230:233], v[86:89]
	v_mfma_f32_16x16x32_bf16 v[46:49], v[10:13], v[234:237], v[46:49]
	ds_read_b128 v[10:13], v116 offset:6144
	ds_read_b128 v[146:149], v124
	ds_read_b128 v[180:183], v124 offset:2048
	ds_read_b128 v[184:187], v124 offset:4096
	ds_read_b128 v[188:191], v124 offset:6144
	ds_read_b128 v[192:195], v124 offset:8192
	ds_read_b128 v[196:199], v124 offset:10240
	ds_read_b128 v[200:203], v124 offset:12288
	ds_read_b128 v[204:207], v124 offset:14336
	s_waitcnt lgkmcnt(8)
	s_waitcnt lgkmcnt(0)
	s_barrier
	v_mfma_f32_16x16x32_bf16 v[170:173], v[14:17], v[216:219], v[170:173]
	v_mfma_f32_16x16x32_bf16 v[130:133], v[14:17], v[226:229], v[130:133]
	v_mfma_f32_16x16x32_bf16 v[82:85], v[14:17], v[230:233], v[82:85]
	v_mfma_f32_16x16x32_bf16 v[34:37], v[14:17], v[234:237], v[34:37]
	v_mfma_f32_16x16x32_bf16 v[166:169], v[38:41], v[216:219], v[166:169]
	v_mfma_f32_16x16x32_bf16 v[126:129], v[38:41], v[226:229], v[126:129]
	v_mfma_f32_16x16x32_bf16 v[78:81], v[38:41], v[230:233], v[78:81]
	v_mfma_f32_16x16x32_bf16 v[30:33], v[38:41], v[234:237], v[30:33]
	v_mfma_f32_16x16x32_bf16 v[162:165], v[62:65], v[216:219], v[162:165]
	v_mfma_f32_16x16x32_bf16 v[118:121], v[62:65], v[226:229], v[118:121]
	v_mfma_f32_16x16x32_bf16 v[74:77], v[62:65], v[230:233], v[74:77]
	v_mfma_f32_16x16x32_bf16 v[26:29], v[62:65], v[234:237], v[26:29]
	v_mfma_f32_16x16x32_bf16 v[158:161], v[66:69], v[216:219], v[158:161]
	v_mfma_f32_16x16x32_bf16 v[110:113], v[66:69], v[226:229], v[110:113]
	v_mfma_f32_16x16x32_bf16 v[70:73], v[66:69], v[230:233], v[70:73]
	v_mfma_f32_16x16x32_bf16 v[22:25], v[66:69], v[234:237], v[22:25]
	v_mfma_f32_16x16x32_bf16 v[154:157], v[90:93], v[216:219], v[154:157]
	v_mfma_f32_16x16x32_bf16 v[106:109], v[90:93], v[226:229], v[106:109]
	v_mfma_f32_16x16x32_bf16 v[58:61], v[90:93], v[230:233], v[58:61]
	v_mfma_f32_16x16x32_bf16 v[18:21], v[90:93], v[234:237], v[18:21]
	v_mfma_f32_16x16x32_bf16 v[150:153], v[94:97], v[216:219], v[150:153]
	v_mfma_f32_16x16x32_bf16 v[102:105], v[94:97], v[226:229], v[102:105]
	v_mfma_f32_16x16x32_bf16 v[54:57], v[94:97], v[230:233], v[54:57]
	v_mfma_f32_16x16x32_bf16 v[6:9], v[94:97], v[234:237], v[6:9]
	v_mfma_f32_16x16x32_bf16 v[138:141], v[142:145], v[216:219], v[138:141]
	v_mfma_f32_16x16x32_bf16 v[98:101], v[142:145], v[226:229], v[98:101]
	v_mfma_f32_16x16x32_bf16 v[50:53], v[142:145], v[230:233], v[50:53]
	v_mfma_f32_16x16x32_bf16 v[2:5], v[142:145], v[234:237], v[2:5]
	v_mfma_f32_16x16x32_bf16 v[174:177], v[146:149], v[238:241], v[174:177]
	v_mfma_f32_16x16x32_bf16 v[134:137], v[146:149], v[242:245], v[134:137]
	v_mfma_f32_16x16x32_bf16 v[86:89], v[146:149], v[246:249], v[86:89]
	v_mfma_f32_16x16x32_bf16 v[46:49], v[146:149], v[10:13], v[46:49]
	v_mfma_f32_16x16x32_bf16 v[170:173], v[180:183], v[238:241], v[170:173]
	v_mfma_f32_16x16x32_bf16 v[130:133], v[180:183], v[242:245], v[130:133]
	v_mfma_f32_16x16x32_bf16 v[82:85], v[180:183], v[246:249], v[82:85]
	v_mfma_f32_16x16x32_bf16 v[34:37], v[180:183], v[10:13], v[34:37]
	v_mfma_f32_16x16x32_bf16 v[166:169], v[184:187], v[238:241], v[166:169]
	v_mfma_f32_16x16x32_bf16 v[126:129], v[184:187], v[242:245], v[126:129]
	v_mfma_f32_16x16x32_bf16 v[78:81], v[184:187], v[246:249], v[78:81]
	v_mfma_f32_16x16x32_bf16 v[30:33], v[184:187], v[10:13], v[30:33]
	v_mfma_f32_16x16x32_bf16 v[162:165], v[188:191], v[238:241], v[162:165]
	v_mfma_f32_16x16x32_bf16 v[118:121], v[188:191], v[242:245], v[118:121]
	v_mfma_f32_16x16x32_bf16 v[74:77], v[188:191], v[246:249], v[74:77]
	v_mfma_f32_16x16x32_bf16 v[26:29], v[188:191], v[10:13], v[26:29]
	v_mfma_f32_16x16x32_bf16 v[158:161], v[192:195], v[238:241], v[158:161]
	v_mfma_f32_16x16x32_bf16 v[110:113], v[192:195], v[242:245], v[110:113]
	v_mfma_f32_16x16x32_bf16 v[70:73], v[192:195], v[246:249], v[70:73]
	v_mfma_f32_16x16x32_bf16 v[22:25], v[192:195], v[10:13], v[22:25]
	v_mfma_f32_16x16x32_bf16 v[154:157], v[196:199], v[238:241], v[154:157]
	v_mfma_f32_16x16x32_bf16 v[106:109], v[196:199], v[242:245], v[106:109]
	v_mfma_f32_16x16x32_bf16 v[58:61], v[196:199], v[246:249], v[58:61]
	v_mfma_f32_16x16x32_bf16 v[18:21], v[196:199], v[10:13], v[18:21]
	v_mfma_f32_16x16x32_bf16 v[150:153], v[200:203], v[238:241], v[150:153]
	v_mfma_f32_16x16x32_bf16 v[102:105], v[200:203], v[242:245], v[102:105]
	v_mfma_f32_16x16x32_bf16 v[54:57], v[200:203], v[246:249], v[54:57]
	v_mfma_f32_16x16x32_bf16 v[6:9], v[200:203], v[10:13], v[6:9]
	v_mfma_f32_16x16x32_bf16 v[138:141], v[204:207], v[238:241], v[138:141]
	v_mfma_f32_16x16x32_bf16 v[98:101], v[204:207], v[242:245], v[98:101]
	v_mfma_f32_16x16x32_bf16 v[50:53], v[204:207], v[246:249], v[50:53]
	v_mfma_f32_16x16x32_bf16 v[2:5], v[204:207], v[10:13], v[2:5]
	s_branch .LBB0_1809
